# act tensor written with default-policy stores instead of nontemporal so the FFN-out A operand can be served from cache
# speedup vs baseline: 1.0046x; 1.0046x over previous
; __device__ __forceinline__ unsigned cvt_pk_bf16(float lo, float hi) { unsigned r; asm volatile("v_cvt_pk_bf16_f32 %0, %1, %2" : "=v"(r) : "v"(lo), "v"(hi)); return r; }
;     __device__ __forceinline__ void operator()(const f32x4 (&acc)[2][2][4][2], const Unit& u, int wr, int wc, int fr, int fq, LAS unsigned char* lds, int tid, int ui, const Unit& nxt, bool has_next) const {
;     ...
;             for (int m = 0; m < 4; ++m) {
;                 const int row = row0 + ai * 128 + m * 16;
;                 const float rs = rsv[ai][m];
;                 typedef float f32x2 __attribute__((ext_vector_type(2)));
;                 const f32x2 rs2 = (f32x2){rs, rs}, nrs2 = (f32x2){-LOG2E * rs, -LOG2E * rs};
;                 unsigned wv[4];
; #pragma unroll
;                 for (int n = 0; n < 2; ++n)
; #pragma unroll
;                     for (int hp = 0; hp < 2; ++hp) {
;                         const f32x2 ag = (f32x2){acc[ai][0][m][n][2 * hp], acc[ai][0][m][n][2 * hp + 1]}, au = (f32x2){acc[ai][1][m][n][2 * hp], acc[ai][1][m][n][2 * hp + 1]};
;                         const f32x2 g = ag * rs2, up = au * rs2, ne = ag * nrs2;
;                         const f32x2 dd = (f32x2){__builtin_amdgcn_exp2f(ne.x), __builtin_amdgcn_exp2f(ne.y)} + 1.0f;
;                         const f32x2 rr = (f32x2){__builtin_amdgcn_rcpf(dd.x), __builtin_amdgcn_rcpf(dd.y)};
;                         const f32x2 oo = (g * rr) * up;
;                         wv[n * 2 + hp] = cvt_pk_bf16(oo.x, oo.y);
;                     }
;                 u32x4 w; w.x = wv[0]; w.y = wv[1]; w.z = wv[2]; w.w = wv[3];
;                 __builtin_nontemporal_store(w, (u32x4*)(O + (size_t)row * FF + col0));
.LBB0_241:
	s_lshl_b32 s4, s58, 10
	s_and_b32 s25, s4, 0x400
	v_add_u32_e32 v148, s25, v163
	ds_read2_b32 v[156:157], v148 offset1:16
	ds_read2_b32 v[152:153], v148 offset0:32 offset1:48
	ds_read2_b32 v[150:151], v148 offset0:128 offset1:144
	ds_read2_b32 v[148:149], v148 offset0:160 offset1:176
	v_lshl_or_b32 v154, s30, 7, v164
	s_waitcnt lgkmcnt(0)
	v_lshl_add_u32 v166, s28, 8, v160
	v_ashrrev_i32_e32 v155, 31, v154
	v_mov_b64_e32 v[186:187], s[16:17]
	v_lshlrev_b64 v[188:189], 1, v[154:155]
	v_mul_f32_e32 v170, 0xbfb8aa3b, v156
	v_mul_f32_e32 v172, v156, v156
	v_add_u32_e32 v167, 0, v166
	v_rcp_f32_e32 v172, v172
	v_mad_i64_i32 v[174:175], s[4:5], v167, s6, v[186:187]
	v_lshl_add_u64 v[174:175], v[174:175], 0, v[188:189]
	v_pk_mul_f32 v[128:129], v[132:133], v[128:129]
	v_pk_mul_f32 v[132:133], v[132:133], v[170:171] op_sel_hi:[1,0]
	v_pk_mul_f32 v[130:131], v[134:135], v[130:131]
	v_pk_mul_f32 v[134:135], v[134:135], v[170:171] op_sel_hi:[1,0]
	v_exp_f32_e32 v132, v132
	v_exp_f32_e32 v133, v133
	v_exp_f32_e32 v134, v134
	v_exp_f32_e32 v135, v135
	v_pk_fma_f32 v[132:133], v[132:133], v[172:173], v[172:173] op_sel_hi:[1,0,0]
	v_pk_fma_f32 v[134:135], v[134:135], v[172:173], v[172:173] op_sel_hi:[1,0,0]
	v_rcp_f32_e32 v132, v132
	v_rcp_f32_e32 v133, v133
	v_rcp_f32_e32 v134, v134
	v_rcp_f32_e32 v135, v135
	v_pk_mul_f32 v[128:129], v[128:129], v[132:133]
	v_pk_mul_f32 v[130:131], v[130:131], v[134:135]
	v_cvt_pk_bf16_f32 v132, v128, v129
	v_cvt_pk_bf16_f32 v133, v130, v131
	v_pk_mul_f32 v[120:121], v[124:125], v[120:121]
	v_pk_mul_f32 v[124:125], v[124:125], v[170:171] op_sel_hi:[1,0]
	v_pk_mul_f32 v[122:123], v[126:127], v[122:123]
	v_pk_mul_f32 v[126:127], v[126:127], v[170:171] op_sel_hi:[1,0]
	v_exp_f32_e32 v124, v124
	v_exp_f32_e32 v125, v125
	v_exp_f32_e32 v126, v126
	v_exp_f32_e32 v127, v127
	v_pk_fma_f32 v[124:125], v[124:125], v[172:173], v[172:173] op_sel_hi:[1,0,0]
	v_pk_fma_f32 v[126:127], v[126:127], v[172:173], v[172:173] op_sel_hi:[1,0,0]
	v_rcp_f32_e32 v124, v124
	v_rcp_f32_e32 v125, v125
	v_rcp_f32_e32 v126, v126
	v_rcp_f32_e32 v127, v127
	v_pk_mul_f32 v[120:121], v[120:121], v[124:125]
	v_pk_mul_f32 v[122:123], v[122:123], v[126:127]
	v_cvt_pk_bf16_f32 v134, v120, v121
	v_cvt_pk_bf16_f32 v135, v122, v123
	global_store_dwordx4 v[174:175], v[132:135], off
	s_cmp_eq_u64 s[22:23], 0
	s_cbranch_scc1 .Lmy_epibar_swiglu
	s_barrier
.Lmy_epibar_swiglu:
	v_mul_f32_e32 v170, 0xbfb8aa3b, v157
	v_mul_f32_e32 v172, v157, v157
	v_add_u32_e32 v167, 16, v166
	v_rcp_f32_e32 v172, v172
	v_mad_i64_i32 v[174:175], s[4:5], v167, s6, v[186:187]
	v_lshl_add_u64 v[174:175], v[174:175], 0, v[188:189]
	v_pk_mul_f32 v[112:113], v[116:117], v[112:113]
	v_pk_mul_f32 v[116:117], v[116:117], v[170:171] op_sel_hi:[1,0]
	v_pk_mul_f32 v[114:115], v[118:119], v[114:115]
	v_pk_mul_f32 v[118:119], v[118:119], v[170:171] op_sel_hi:[1,0]
	v_exp_f32_e32 v116, v116
	v_exp_f32_e32 v117, v117
	v_exp_f32_e32 v118, v118
	v_exp_f32_e32 v119, v119
	v_pk_fma_f32 v[116:117], v[116:117], v[172:173], v[172:173] op_sel_hi:[1,0,0]
	v_pk_fma_f32 v[118:119], v[118:119], v[172:173], v[172:173] op_sel_hi:[1,0,0]
	v_rcp_f32_e32 v116, v116
	v_rcp_f32_e32 v117, v117
	v_rcp_f32_e32 v118, v118
	v_rcp_f32_e32 v119, v119
	v_pk_mul_f32 v[112:113], v[112:113], v[116:117]
	v_pk_mul_f32 v[114:115], v[114:115], v[118:119]
	v_cvt_pk_bf16_f32 v116, v112, v113
	v_cvt_pk_bf16_f32 v117, v114, v115
	v_pk_mul_f32 v[104:105], v[108:109], v[104:105]
	v_pk_mul_f32 v[108:109], v[108:109], v[170:171] op_sel_hi:[1,0]
	v_pk_mul_f32 v[106:107], v[110:111], v[106:107]
	v_pk_mul_f32 v[110:111], v[110:111], v[170:171] op_sel_hi:[1,0]
	v_exp_f32_e32 v108, v108
	v_exp_f32_e32 v109, v109
	v_exp_f32_e32 v110, v110
	v_exp_f32_e32 v111, v111
	v_pk_fma_f32 v[108:109], v[108:109], v[172:173], v[172:173] op_sel_hi:[1,0,0]
	v_pk_fma_f32 v[110:111], v[110:111], v[172:173], v[172:173] op_sel_hi:[1,0,0]
	v_rcp_f32_e32 v108, v108
	v_rcp_f32_e32 v109, v109
	v_rcp_f32_e32 v110, v110
	v_rcp_f32_e32 v111, v111
	v_pk_mul_f32 v[104:105], v[104:105], v[108:109]
	v_pk_mul_f32 v[106:107], v[106:107], v[110:111]
	v_cvt_pk_bf16_f32 v118, v104, v105
	v_cvt_pk_bf16_f32 v119, v106, v107
	global_store_dwordx4 v[174:175], v[116:119], off
	v_mul_f32_e32 v170, 0xbfb8aa3b, v152
	v_mul_f32_e32 v172, v152, v152
	v_add_u32_e32 v167, 32, v166
	v_rcp_f32_e32 v172, v172
	v_mad_i64_i32 v[174:175], s[4:5], v167, s6, v[186:187]
	v_lshl_add_u64 v[174:175], v[174:175], 0, v[188:189]
	v_pk_mul_f32 v[96:97], v[100:101], v[96:97]
	v_pk_mul_f32 v[100:101], v[100:101], v[170:171] op_sel_hi:[1,0]
	v_pk_mul_f32 v[98:99], v[102:103], v[98:99]
	v_pk_mul_f32 v[102:103], v[102:103], v[170:171] op_sel_hi:[1,0]
	v_exp_f32_e32 v100, v100
	v_exp_f32_e32 v101, v101
	v_exp_f32_e32 v102, v102
	v_exp_f32_e32 v103, v103
	v_pk_fma_f32 v[100:101], v[100:101], v[172:173], v[172:173] op_sel_hi:[1,0,0]
	v_pk_fma_f32 v[102:103], v[102:103], v[172:173], v[172:173] op_sel_hi:[1,0,0]
	v_rcp_f32_e32 v100, v100
	v_rcp_f32_e32 v101, v101
	v_rcp_f32_e32 v102, v102
	v_rcp_f32_e32 v103, v103
	v_pk_mul_f32 v[96:97], v[96:97], v[100:101]
	v_pk_mul_f32 v[98:99], v[98:99], v[102:103]
	v_cvt_pk_bf16_f32 v100, v96, v97
	v_cvt_pk_bf16_f32 v101, v98, v99
	v_pk_mul_f32 v[88:89], v[92:93], v[88:89]
	v_pk_mul_f32 v[92:93], v[92:93], v[170:171] op_sel_hi:[1,0]
	v_pk_mul_f32 v[90:91], v[94:95], v[90:91]
	v_pk_mul_f32 v[94:95], v[94:95], v[170:171] op_sel_hi:[1,0]
	v_exp_f32_e32 v92, v92
	v_exp_f32_e32 v93, v93
	v_exp_f32_e32 v94, v94
	v_exp_f32_e32 v95, v95
	v_pk_fma_f32 v[92:93], v[92:93], v[172:173], v[172:173] op_sel_hi:[1,0,0]
	v_pk_fma_f32 v[94:95], v[94:95], v[172:173], v[172:173] op_sel_hi:[1,0,0]
; __device__ __forceinline__ unsigned cvt_pk_bf16(float lo, float hi) { unsigned r; asm volatile("v_cvt_pk_bf16_f32 %0, %1, %2" : "=v"(r) : "v"(lo), "v"(hi)); return r; }
;     __device__ __forceinline__ void operator()(const f32x4 (&acc)[2][2][4][2], const Unit& u, int wr, int wc, int fr, int fq, LAS unsigned char* lds, int tid, int ui, const Unit& nxt, bool has_next) const {
;     ...
; #pragma unroll
;                 for (int n = 0; n < 2; ++n)
; #pragma unroll
;                     for (int hp = 0; hp < 2; ++hp) {
;                         const f32x2 ag = (f32x2){acc[ai][0][m][n][2 * hp], acc[ai][0][m][n][2 * hp + 1]}, au = (f32x2){acc[ai][1][m][n][2 * hp], acc[ai][1][m][n][2 * hp + 1]};
;                         const f32x2 g = ag * rs2, up = au * rs2, ne = ag * nrs2;
;                         const f32x2 dd = (f32x2){__builtin_amdgcn_exp2f(ne.x), __builtin_amdgcn_exp2f(ne.y)} + 1.0f;
;                         const f32x2 rr = (f32x2){__builtin_amdgcn_rcpf(dd.x), __builtin_amdgcn_rcpf(dd.y)};
;                         const f32x2 oo = (g * rr) * up;
;                         wv[n * 2 + hp] = cvt_pk_bf16(oo.x, oo.y);
;                     }
;                 u32x4 w; w.x = wv[0]; w.y = wv[1]; w.z = wv[2]; w.w = wv[3];
;                 __builtin_nontemporal_store(w, (u32x4*)(O + (size_t)row * FF + col0));
	v_rcp_f32_e32 v92, v92
	v_rcp_f32_e32 v93, v93
	v_rcp_f32_e32 v94, v94
	v_rcp_f32_e32 v95, v95
	v_pk_mul_f32 v[88:89], v[88:89], v[92:93]
	v_pk_mul_f32 v[90:91], v[90:91], v[94:95]
	v_cvt_pk_bf16_f32 v102, v88, v89
	v_cvt_pk_bf16_f32 v103, v90, v91
	global_store_dwordx4 v[174:175], v[100:103], off
	v_mul_f32_e32 v170, 0xbfb8aa3b, v153
	v_mul_f32_e32 v172, v153, v153
	v_add_u32_e32 v167, 48, v166
	v_rcp_f32_e32 v172, v172
	v_mad_i64_i32 v[174:175], s[4:5], v167, s6, v[186:187]
	v_lshl_add_u64 v[174:175], v[174:175], 0, v[188:189]
	v_pk_mul_f32 v[80:81], v[84:85], v[80:81]
	v_pk_mul_f32 v[84:85], v[84:85], v[170:171] op_sel_hi:[1,0]
	v_pk_mul_f32 v[82:83], v[86:87], v[82:83]
	v_pk_mul_f32 v[86:87], v[86:87], v[170:171] op_sel_hi:[1,0]
	v_exp_f32_e32 v84, v84
	v_exp_f32_e32 v85, v85
	v_exp_f32_e32 v86, v86
	v_exp_f32_e32 v87, v87
	v_pk_fma_f32 v[84:85], v[84:85], v[172:173], v[172:173] op_sel_hi:[1,0,0]
	v_pk_fma_f32 v[86:87], v[86:87], v[172:173], v[172:173] op_sel_hi:[1,0,0]
	v_rcp_f32_e32 v84, v84
	v_rcp_f32_e32 v85, v85
	v_rcp_f32_e32 v86, v86
	v_rcp_f32_e32 v87, v87
	v_pk_mul_f32 v[80:81], v[80:81], v[84:85]
	v_pk_mul_f32 v[82:83], v[82:83], v[86:87]
	v_cvt_pk_bf16_f32 v84, v80, v81
	v_cvt_pk_bf16_f32 v85, v82, v83
	v_pk_mul_f32 v[72:73], v[76:77], v[72:73]
	v_pk_mul_f32 v[76:77], v[76:77], v[170:171] op_sel_hi:[1,0]
	v_pk_mul_f32 v[74:75], v[78:79], v[74:75]
	v_pk_mul_f32 v[78:79], v[78:79], v[170:171] op_sel_hi:[1,0]
	v_exp_f32_e32 v76, v76
	v_exp_f32_e32 v77, v77
	v_exp_f32_e32 v78, v78
	v_exp_f32_e32 v79, v79
	v_pk_fma_f32 v[76:77], v[76:77], v[172:173], v[172:173] op_sel_hi:[1,0,0]
	v_pk_fma_f32 v[78:79], v[78:79], v[172:173], v[172:173] op_sel_hi:[1,0,0]
	v_rcp_f32_e32 v76, v76
	v_rcp_f32_e32 v77, v77
	v_rcp_f32_e32 v78, v78
	v_rcp_f32_e32 v79, v79
	v_pk_mul_f32 v[72:73], v[72:73], v[76:77]
	v_pk_mul_f32 v[74:75], v[74:75], v[78:79]
	v_cvt_pk_bf16_f32 v86, v72, v73
	v_cvt_pk_bf16_f32 v87, v74, v75
	global_store_dwordx4 v[174:175], v[84:87], off
	v_mul_f32_e32 v170, 0xbfb8aa3b, v150
	v_mul_f32_e32 v172, v150, v150
	v_add_u32_e32 v167, 128, v166
	v_rcp_f32_e32 v172, v172
	v_mad_i64_i32 v[174:175], s[4:5], v167, s6, v[186:187]
	v_lshl_add_u64 v[174:175], v[174:175], 0, v[188:189]
	v_pk_mul_f32 v[64:65], v[68:69], v[64:65]
	v_pk_mul_f32 v[68:69], v[68:69], v[170:171] op_sel_hi:[1,0]
	v_pk_mul_f32 v[66:67], v[70:71], v[66:67]
	v_pk_mul_f32 v[70:71], v[70:71], v[170:171] op_sel_hi:[1,0]
	v_exp_f32_e32 v68, v68
	v_exp_f32_e32 v69, v69
	v_exp_f32_e32 v70, v70
	v_exp_f32_e32 v71, v71
	v_pk_fma_f32 v[68:69], v[68:69], v[172:173], v[172:173] op_sel_hi:[1,0,0]
	v_pk_fma_f32 v[70:71], v[70:71], v[172:173], v[172:173] op_sel_hi:[1,0,0]
	v_rcp_f32_e32 v68, v68
	v_rcp_f32_e32 v69, v69
	v_rcp_f32_e32 v70, v70
	v_rcp_f32_e32 v71, v71
	v_pk_mul_f32 v[64:65], v[64:65], v[68:69]
	v_pk_mul_f32 v[66:67], v[66:67], v[70:71]
	v_cvt_pk_bf16_f32 v68, v64, v65
	v_cvt_pk_bf16_f32 v69, v66, v67
	v_pk_mul_f32 v[48:49], v[52:53], v[48:49]
	v_pk_mul_f32 v[52:53], v[52:53], v[170:171] op_sel_hi:[1,0]
	v_pk_mul_f32 v[50:51], v[54:55], v[50:51]
	v_pk_mul_f32 v[54:55], v[54:55], v[170:171] op_sel_hi:[1,0]
	v_exp_f32_e32 v52, v52
	v_exp_f32_e32 v53, v53
	v_exp_f32_e32 v54, v54
	v_exp_f32_e32 v55, v55
	v_pk_fma_f32 v[52:53], v[52:53], v[172:173], v[172:173] op_sel_hi:[1,0,0]
	v_pk_fma_f32 v[54:55], v[54:55], v[172:173], v[172:173] op_sel_hi:[1,0,0]
	v_rcp_f32_e32 v52, v52
	v_rcp_f32_e32 v53, v53
	v_rcp_f32_e32 v54, v54
	v_rcp_f32_e32 v55, v55
	v_pk_mul_f32 v[48:49], v[48:49], v[52:53]
	v_pk_mul_f32 v[50:51], v[50:51], v[54:55]
	v_cvt_pk_bf16_f32 v70, v48, v49
	v_cvt_pk_bf16_f32 v71, v50, v51
	global_store_dwordx4 v[174:175], v[68:71], off
	v_mul_f32_e32 v170, 0xbfb8aa3b, v151
	v_mul_f32_e32 v172, v151, v151
	v_add_u32_e32 v167, 144, v166
	v_rcp_f32_e32 v172, v172
	v_mad_i64_i32 v[174:175], s[4:5], v167, s6, v[186:187]
	v_lshl_add_u64 v[174:175], v[174:175], 0, v[188:189]
	v_pk_mul_f32 v[40:41], v[44:45], v[40:41]
	v_pk_mul_f32 v[44:45], v[44:45], v[170:171] op_sel_hi:[1,0]
	v_pk_mul_f32 v[42:43], v[46:47], v[42:43]
	v_pk_mul_f32 v[46:47], v[46:47], v[170:171] op_sel_hi:[1,0]
	v_exp_f32_e32 v44, v44
	v_exp_f32_e32 v45, v45
	v_exp_f32_e32 v46, v46
	v_exp_f32_e32 v47, v47
	v_pk_fma_f32 v[44:45], v[44:45], v[172:173], v[172:173] op_sel_hi:[1,0,0]
	v_pk_fma_f32 v[46:47], v[46:47], v[172:173], v[172:173] op_sel_hi:[1,0,0]
	v_rcp_f32_e32 v44, v44
	v_rcp_f32_e32 v45, v45
	v_rcp_f32_e32 v46, v46
	v_rcp_f32_e32 v47, v47
	v_pk_mul_f32 v[40:41], v[40:41], v[44:45]
	v_pk_mul_f32 v[42:43], v[42:43], v[46:47]
	v_cvt_pk_bf16_f32 v44, v40, v41
	v_cvt_pk_bf16_f32 v45, v42, v43
	v_pk_mul_f32 v[32:33], v[36:37], v[32:33]
	v_pk_mul_f32 v[36:37], v[36:37], v[170:171] op_sel_hi:[1,0]
; __device__ __forceinline__ unsigned cvt_pk_bf16(float lo, float hi) { unsigned r; asm volatile("v_cvt_pk_bf16_f32 %0, %1, %2" : "=v"(r) : "v"(lo), "v"(hi)); return r; }
; #define LAS __attribute__((address_space(3)))
; __device__ __forceinline__ void rs_finish(LAS unsigned char* lds, int buf, int tid, const f32x4& a, const f32x4& b) {
;     float t = ((a.x + a.y) + (a.z + a.w)) + ((b.x + b.y) + (b.z + b.w)); t += __shfl_xor(t, 1);
;     if (!(tid & 1)) ((LAS float*)(lds + RS_LDS_OFF))[buf * 256 + (tid >> 1)] = rsqrtf(t * (1.f / D) + RMS_EPS);
;     __device__ __forceinline__ void operator()(const f32x4 (&acc)[2][2][4][2], const Unit& u, int wr, int wc, int fr, int fq, LAS unsigned char* lds, int tid, int ui, const Unit& nxt, bool has_next) const {
;     ...
; #pragma unroll
;                 for (int n = 0; n < 2; ++n)
; #pragma unroll
;                     for (int hp = 0; hp < 2; ++hp) {
;                         const f32x2 ag = (f32x2){acc[ai][0][m][n][2 * hp], acc[ai][0][m][n][2 * hp + 1]}, au = (f32x2){acc[ai][1][m][n][2 * hp], acc[ai][1][m][n][2 * hp + 1]};
;                         const f32x2 g = ag * rs2, up = au * rs2, ne = ag * nrs2;
;                         const f32x2 dd = (f32x2){__builtin_amdgcn_exp2f(ne.x), __builtin_amdgcn_exp2f(ne.y)} + 1.0f;
;                         const f32x2 rr = (f32x2){__builtin_amdgcn_rcpf(dd.x), __builtin_amdgcn_rcpf(dd.y)};
;                         const f32x2 oo = (g * rr) * up;
;                         wv[n * 2 + hp] = cvt_pk_bf16(oo.x, oo.y);
;                     }
;                 u32x4 w; w.x = wv[0]; w.y = wv[1]; w.z = wv[2]; w.w = wv[3];
;                 __builtin_nontemporal_store(w, (u32x4*)(O + (size_t)row * FF + col0));
	v_pk_mul_f32 v[34:35], v[38:39], v[34:35]
	v_pk_mul_f32 v[38:39], v[38:39], v[170:171] op_sel_hi:[1,0]
	v_exp_f32_e32 v36, v36
	v_exp_f32_e32 v37, v37
	v_exp_f32_e32 v38, v38
	v_exp_f32_e32 v39, v39
	v_pk_fma_f32 v[36:37], v[36:37], v[172:173], v[172:173] op_sel_hi:[1,0,0]
	v_pk_fma_f32 v[38:39], v[38:39], v[172:173], v[172:173] op_sel_hi:[1,0,0]
	v_rcp_f32_e32 v36, v36
	v_rcp_f32_e32 v37, v37
	v_rcp_f32_e32 v38, v38
	v_rcp_f32_e32 v39, v39
	v_pk_mul_f32 v[32:33], v[32:33], v[36:37]
	v_pk_mul_f32 v[34:35], v[34:35], v[38:39]
	v_cvt_pk_bf16_f32 v46, v32, v33
	v_cvt_pk_bf16_f32 v47, v34, v35
	global_store_dwordx4 v[174:175], v[44:47], off
	v_mul_f32_e32 v170, 0xbfb8aa3b, v148
	v_mul_f32_e32 v172, v148, v148
	v_add_u32_e32 v167, 160, v166
	v_rcp_f32_e32 v172, v172
	v_mad_i64_i32 v[174:175], s[4:5], v167, s6, v[186:187]
	v_lshl_add_u64 v[174:175], v[174:175], 0, v[188:189]
	v_pk_mul_f32 v[24:25], v[28:29], v[24:25]
	v_pk_mul_f32 v[28:29], v[28:29], v[170:171] op_sel_hi:[1,0]
	v_pk_mul_f32 v[26:27], v[30:31], v[26:27]
	v_pk_mul_f32 v[30:31], v[30:31], v[170:171] op_sel_hi:[1,0]
	v_exp_f32_e32 v28, v28
	v_exp_f32_e32 v29, v29
	v_exp_f32_e32 v30, v30
	v_exp_f32_e32 v31, v31
	v_pk_fma_f32 v[28:29], v[28:29], v[172:173], v[172:173] op_sel_hi:[1,0,0]
	v_pk_fma_f32 v[30:31], v[30:31], v[172:173], v[172:173] op_sel_hi:[1,0,0]
	v_rcp_f32_e32 v28, v28
	v_rcp_f32_e32 v29, v29
	v_rcp_f32_e32 v30, v30
	v_rcp_f32_e32 v31, v31
	v_pk_mul_f32 v[24:25], v[24:25], v[28:29]
	v_pk_mul_f32 v[26:27], v[26:27], v[30:31]
	v_cvt_pk_bf16_f32 v28, v24, v25
	v_cvt_pk_bf16_f32 v29, v26, v27
	v_pk_mul_f32 v[16:17], v[20:21], v[16:17]
	v_pk_mul_f32 v[20:21], v[20:21], v[170:171] op_sel_hi:[1,0]
	v_pk_mul_f32 v[18:19], v[22:23], v[18:19]
	v_pk_mul_f32 v[22:23], v[22:23], v[170:171] op_sel_hi:[1,0]
	v_exp_f32_e32 v20, v20
	v_exp_f32_e32 v21, v21
	v_exp_f32_e32 v22, v22
	v_exp_f32_e32 v23, v23
	v_pk_fma_f32 v[20:21], v[20:21], v[172:173], v[172:173] op_sel_hi:[1,0,0]
	v_pk_fma_f32 v[22:23], v[22:23], v[172:173], v[172:173] op_sel_hi:[1,0,0]
	v_rcp_f32_e32 v20, v20
	v_rcp_f32_e32 v21, v21
	v_rcp_f32_e32 v22, v22
	v_rcp_f32_e32 v23, v23
	v_pk_mul_f32 v[16:17], v[16:17], v[20:21]
	v_pk_mul_f32 v[18:19], v[18:19], v[22:23]
	v_cvt_pk_bf16_f32 v30, v16, v17
	v_cvt_pk_bf16_f32 v31, v18, v19
	global_store_dwordx4 v[174:175], v[28:31], off
	v_mul_f32_e32 v170, 0xbfb8aa3b, v149
	v_mul_f32_e32 v172, v149, v149
	v_add_u32_e32 v167, 176, v166
	v_rcp_f32_e32 v172, v172
	v_mad_i64_i32 v[174:175], s[4:5], v167, s6, v[186:187]
	v_lshl_add_u64 v[174:175], v[174:175], 0, v[188:189]
	v_pk_mul_f32 v[8:9], v[12:13], v[8:9]
	v_pk_mul_f32 v[12:13], v[12:13], v[170:171] op_sel_hi:[1,0]
	v_pk_mul_f32 v[10:11], v[14:15], v[10:11]
	v_pk_mul_f32 v[14:15], v[14:15], v[170:171] op_sel_hi:[1,0]
	v_exp_f32_e32 v12, v12
	v_exp_f32_e32 v13, v13
	v_exp_f32_e32 v14, v14
	v_exp_f32_e32 v15, v15
	v_pk_fma_f32 v[12:13], v[12:13], v[172:173], v[172:173] op_sel_hi:[1,0,0]
	v_pk_fma_f32 v[14:15], v[14:15], v[172:173], v[172:173] op_sel_hi:[1,0,0]
	v_rcp_f32_e32 v12, v12
	v_rcp_f32_e32 v13, v13
	v_rcp_f32_e32 v14, v14
	v_rcp_f32_e32 v15, v15
	v_pk_mul_f32 v[8:9], v[8:9], v[12:13]
	v_pk_mul_f32 v[10:11], v[10:11], v[14:15]
	v_cvt_pk_bf16_f32 v12, v8, v9
	v_cvt_pk_bf16_f32 v13, v10, v11
	v_pk_mul_f32 v[0:1], v[4:5], v[0:1]
	v_pk_mul_f32 v[4:5], v[4:5], v[170:171] op_sel_hi:[1,0]
	v_pk_mul_f32 v[2:3], v[6:7], v[2:3]
	v_pk_mul_f32 v[6:7], v[6:7], v[170:171] op_sel_hi:[1,0]
	v_exp_f32_e32 v4, v4
	v_exp_f32_e32 v5, v5
	v_exp_f32_e32 v6, v6
	v_exp_f32_e32 v7, v7
	v_pk_fma_f32 v[4:5], v[4:5], v[172:173], v[172:173] op_sel_hi:[1,0,0]
	v_pk_fma_f32 v[6:7], v[6:7], v[172:173], v[172:173] op_sel_hi:[1,0,0]
	v_rcp_f32_e32 v4, v4
	v_rcp_f32_e32 v5, v5
	v_rcp_f32_e32 v6, v6
	v_rcp_f32_e32 v7, v7
	v_pk_mul_f32 v[0:1], v[0:1], v[4:5]
	v_pk_mul_f32 v[2:3], v[2:3], v[6:7]
	v_cvt_pk_bf16_f32 v14, v0, v1
	v_cvt_pk_bf16_f32 v15, v2, v3
	global_store_dwordx4 v[174:175], v[12:15], off
	s_and_b64 vcc, exec, s[40:41]
	s_mov_b64 s[4:5], -1
	s_cbranch_vccnz .LBB0_232
	s_waitcnt vmcnt(8)
	v_add_f32_e32 v0, v60, v61
	v_add_f32_e32 v1, v62, v63
	v_add_f32_e32 v0, v0, v1
	v_add_f32_e32 v1, v56, v57
	v_add_f32_e32 v2, v58, v59
	v_add_f32_e32 v1, v1, v2
	v_add_f32_e32 v0, v1, v0
	ds_bpermute_b32 v1, v159, v0
	s_and_saveexec_b64 s[4:5], s[38:39]
	s_cbranch_execz .LBB0_244
	s_waitcnt lgkmcnt(0)
	v_add_f32_e32 v0, v0, v1
	v_fmamk_f32 v0, v0, 0x3a800000, v222
	v_cmp_gt_f32_e32 vcc, s7, v0
	v_mul_f32_e32 v1, 0x4b800000, v0
	s_xor_b32 s25, s25, 0x400
	v_cndmask_b32_e32 v0, v0, v1, vcc
	v_rsq_f32_e32 v0, v0
	s_nop 0
	v_mul_f32_e32 v1, 0x45800000, v0
	v_cndmask_b32_e32 v0, v0, v1, vcc
	v_add_u32_e32 v1, s25, v162
	ds_write_b32 v1, v0
